# k17: k16 + static s_setprio 1 for waves 4-7 during GEMM phases
# speedup vs baseline: 1.0134x; 1.0021x over previous
; __device__ __forceinline__ int opaque_tid() { int t = threadIdx.x; asm volatile("" : "+v"(t)); return t; }
; #define PG8_STAGE(bufoff, gbase, voff) do { _Pragma("unroll") for (int _i = 0; _i < 2; ++_i) \
;         __builtin_amdgcn_global_load_lds((const unsigned*)((const char*)(gbase) + (voff)[_i]), (LAS unsigned*)(lds + (bufoff) + ldsw + _i * 8192), 16, 0, 0); } while (0)
; #define PG8_WAIT_V(n) asm volatile("s_waitcnt vmcnt(" #n ")" ::: "memory")
; #define PG8_BAR __builtin_amdgcn_s_barrier()
; template <class Epi>
; __device__ __forceinline__ void gemm_phase(LAS unsigned char* lds, const Gemm g, const Epi& E) {
;     const int tid = opaque_tid(), wid = __builtin_amdgcn_readfirstlane(tid >> 6), lane = tid & 63, wr = wid >> 2, wc = wid & 3, fr = lane & 15, fq = lane >> 4;
;     const int K = g.K, nt = K / BK;
;     StaticOrder S; S.init(g.M, g.N, (int)gridDim.x, (int)blockIdx.x);
;     unsigned voffA[2], voffB[2];
; #pragma unroll
;     for (int i = 0; i < 2; ++i) { int R, C; stage_rc(tid * 16 + i * 8192, R, C); const int Rb = Epi::PERM ? ((R & ~31) + perm32(R & 31)) : R;
;         voffA[i] = (unsigned)(R * g.lda + C) * 2u; voffB[i] = (unsigned)(Rb * g.ldb + C) * 2u; }
;     const size_t kstep = (size_t)(BK * 2);
;     const size_t hstepA = (size_t)HALF * g.lda * 2, hstepB = (size_t)HALF * g.ldb * 2;
;     const size_t tstepA = 2 * hstepA, tstepB = 2 * hstepB;
;     const unsigned ldsw = (unsigned)wid * 1024u;
;     const int aoff = lds_byte(wr * 64 + fr, fq * 8), boff = lds_byte(wc * 32 + fr, fq * 8);
;     ...
;     Unit cur, nxt; int ui = 0;
;     if (!S.next(0, cur)) return;
;     f32x4 acc[2][2][4][2];
; #pragma unroll
;     for (int a = 0; a < 2; ++a)
; #pragma unroll
;         for (int b = 0; b < 2; ++b)
; #pragma unroll
;             for (int m = 0; m < 4; ++m)
; #pragma unroll
;                 for (int n = 0; n < 2; ++n) acc[a][b][m][n] = (f32x4){0.f, 0.f, 0.f, 0.f};
;     bf16x8 At[4][2], B0[2][2], B1[2][2];
;     const char* cA = (const char*)g.A + (size_t)g.mapA.src(cur.pm) * tstepA + (size_t)cur.pn * g.a_pn_step;
;     const char* cB = (const char*)g.Bt + (size_t)g.mapB.src(cur.pn) * tstepB;
;     PG8_STAGE(PG8_SB(0, 0), cB, voffB); PG8_STAGE(PG8_SA(0, 0), cA, voffA); PG8_STAGE(PG8_SB(0, 1), cB + hstepB, voffB); PG8_STAGE(PG8_SA(0, 1), cA + hstepA, voffA);
;     if (wr == 1) PG8_BAR;
;     PG8_WAIT_V(4); PG8_BAR;
.LBB0_286:
	s_or_b64 exec, exec, s[2:3]
	s_and_b64 s[0:1], s[8:9], exec
	s_movk_i32 s0, 0x120
	s_cselect_b32 s7, 0x100, s0
	v_mov_b32_e32 v2, v210
	s_lshl_b32 s76, s7, 2
	s_barrier
	s_cmp_ge_i32 s37, s76
	v_readfirstlane_b32 s2, v2
	s_cbranch_scc1 .LBB0_310
	v_lshlrev_b32_e32 v1, 4, v2
	v_add_u32_e32 v3, 0x2000, v1
	v_ashrrev_i32_e32 v4, 31, v3
	v_lshrrev_b32_e32 v4, 22, v4
	v_add_u32_e32 v4, v3, v4
	v_ashrrev_i32_e32 v4, 10, v4
	v_mul_i32_i24_e32 v6, 0x400, v4
	v_sub_u32_e32 v3, v3, v6
	v_lshrrev_b32_e32 v6, 4, v3
	v_bitop3_b32 v3, v6, v3, 32 bitop3:0x6c
	v_ashrrev_i32_e32 v6, 31, v3
	v_writelane_b32 v255, s10, 30
	v_lshrrev_b32_e32 v6, 26, v6
	v_readlane_b32 s0, v255, 21
	v_add_u32_e32 v6, v3, v6
	v_readlane_b32 s1, v255, 22
	v_lshlrev_b32_e32 v5, 5, v4
	v_ashrrev_i32_e32 v7, 6, v6
	v_and_b32_e32 v6, 0xc0, v6
	v_lshlrev_b32_e32 v4, 3, v4
	s_lshl_b32 s0, s0, 19
	v_readlane_b32 s1, v254, 28
	v_sub_u32_e32 v3, v3, v6
	v_and_b32_e32 v4, -16, v4
	s_add_u32 s13, s1, s0
	v_readlane_b32 s0, v254, 29
	v_and_b32_e32 v5, 32, v5
	v_ashrrev_i16_sdwa v3, v219, sext(v3) dst_sel:DWORD dst_unused:UNUSED_PAD src0_sel:DWORD src1_sel:BYTE_0
	v_add_u32_e32 v4, v7, v4
	s_addc_u32 s25, s0, 0
	s_ashr_i32 s0, s2, 6
	v_add_u32_sdwa v3, v5, sext(v3) dst_sel:DWORD dst_unused:UNUSED_PAD src0_sel:DWORD src1_sel:WORD_0
	v_lshlrev_b32_e32 v5, 9, v4
	s_ashr_i32 s1, s2, 8
	s_lshl_b32 s30, s0, 10
	v_lshl_add_u32 v146, v3, 1, v5
	s_movk_i32 s11, 0x600
	v_writelane_b32 v255, s2, 31
	s_and_b64 s[2:3], s[8:9], exec
	v_mad_u64_u32 v[148:149], s[2:3], v4, s11, v[146:147]
	v_bfe_i32 v5, v2, 27, 1
	s_cselect_b32 s31, 0, 2.0
	v_lshrrev_b32_e32 v5, 22, v5
	s_lshr_b32 s3, s7, 1
	v_readlane_b32 s2, v254, 49
	v_add_u32_e32 v5, v1, v5
	s_or_b32 s2, s3, s2
	v_and_b32_e32 v5, 0xfffffc00, v5
	s_mul_i32 s2, s2, s80
	v_sub_u32_e32 v1, v1, v5
	s_add_i32 s4, s2, s75
	v_lshrrev_b32_e32 v5, 4, v1
	s_ashr_i32 s2, s4, 31
	v_bitop3_b32 v5, v5, v1, 32 bitop3:0x6c
	v_ashrrev_i32_e32 v1, 31, v1
	s_lshr_b32 s2, s2, 28
	v_ashrrev_i32_e32 v3, 31, v2
	v_lshrrev_b32_e32 v1, 26, v1
	s_add_i32 s5, s4, s2
	v_lshrrev_b32_e32 v3, 26, v3
	v_add_u32_e32 v1, v5, v1
	s_ashr_i32 s2, s5, 4
	v_add_u32_e32 v3, v2, v3
	v_ashrrev_i32_e32 v1, 6, v1
	s_lshl_b32 s6, s2, 2
	v_ashrrev_i32_e32 v3, 6, v3
	v_mul_i32_i24_e32 v6, 64, v1
	v_writelane_b32 v255, s3, 29
	s_sub_i32 s2, s7, s6
	v_lshlrev_b32_e32 v4, 5, v3
	v_sub_u32_e32 v5, v5, v6
	v_writelane_b32 v255, s7, 28
	s_min_i32 s7, s2, 4
	v_and_b32_e32 v4, 32, v4
	v_ashrrev_i16_sdwa v5, v219, sext(v5) dst_sel:DWORD dst_unused:UNUSED_PAD src0_sel:DWORD src1_sel:BYTE_0
	v_lshlrev_b32_e32 v3, 3, v3
	s_abs_i32 s10, s7
	v_add_u32_sdwa v4, v4, sext(v5) dst_sel:DWORD dst_unused:UNUSED_PAD src0_sel:DWORD src1_sel:WORD_0
	v_and_b32_e32 v3, -16, v3
	v_cvt_f32_u32_e32 v5, s10
	v_add_u32_e32 v1, v1, v3
	v_lshlrev_b32_e32 v3, 9, v1
	v_lshl_add_u32 v150, v4, 1, v3
	v_mad_u64_u32 v[152:153], s[2:3], v1, s11, v[150:151]
	v_rcp_iflag_f32_e32 v1, v5
	s_and_b32 s2, s5, -16
	s_sub_i32 s5, 0, s10
	s_sub_i32 s2, s4, s2
	v_mul_f32_e32 v1, 0x4f7ffffe, v1
	v_cvt_u32_f32_e32 v1, v1
	s_abs_i32 s4, s2
	s_xor_b32 s3, s2, s7
	s_ashr_i32 s3, s3, 31
	v_readfirstlane_b32 s11, v1
	s_mul_i32 s5, s5, s11
	s_mul_hi_u32 s5, s11, s5
	s_add_i32 s11, s11, s5
	s_mul_hi_u32 s5, s4, s11
	s_mul_i32 s11, s5, s10
	s_sub_i32 s4, s4, s11
	s_add_i32 s11, s5, 1
	s_sub_i32 s12, s4, s10
	s_cmp_ge_u32 s4, s10
	s_cselect_b32 s5, s11, s5
	s_cselect_b32 s4, s12, s4
	s_add_i32 s11, s5, 1
	s_cmp_ge_u32 s4, s10
	s_cselect_b32 s4, s11, s5
	s_xor_b32 s4, s4, s3
	s_sub_i32 s4, s4, s3
	s_mul_i32 s3, s4, s7
	s_sub_i32 s2, s2, s3
	s_add_i32 s93, s6, s2
	s_and_b64 s[2:3], s[8:9], exec
	s_cselect_b32 s44, 32, -2.0
	s_cmp_ge_i32 s93, s31
	s_cselect_b32 s2, s44, 0
	s_add_i32 s2, s2, s93
	s_ashr_i32 s3, s2, 31
	s_ashr_i32 s5, s4, 31
	s_lshl_b64 s[2:3], s[2:3], 19
	s_lshl_b64 s[6:7], s[4:5], 9
	s_lshl_b64 s[8:9], s[4:5], 17
	s_add_u32 s14, s13, s8
	s_addc_u32 s15, s25, s9
	s_add_i32 s26, s30, 0
	s_add_i32 m0, s26, 0x10000
	s_mov_b32 s91, s13
	global_load_lds_dwordx4 v150, s[14:15]
	s_add_i32 m0, s26, 0x12000
	s_add_u32 s2, s34, s2
	s_addc_u32 s3, s35, s3
	s_add_u32 s16, s2, s6
	global_load_lds_dwordx4 v146, s[14:15]
	s_addc_u32 s17, s3, s7
	s_mov_b32 m0, s26
	s_add_i32 s52, s26, 0x2000
	global_load_lds_dwordx4 v152, s[16:17]
	s_mov_b32 m0, s52
	s_add_u32 s2, s14, 0x10000
	global_load_lds_dwordx4 v148, s[16:17]
	s_addc_u32 s3, s15, 0
	s_add_i32 m0, s26, 0x14000
	s_nop 0
	global_load_lds_dwordx4 v150, s[2:3]
	s_add_i32 m0, s26, 0x16000
	s_nop 0
	global_load_lds_dwordx4 v146, s[2:3]
	s_add_u32 s2, s16, 0x40000
	s_addc_u32 s3, s17, 0
	s_add_i32 s53, s26, 0x4000
	s_mov_b32 m0, s53
	s_add_i32 s68, s26, 0x6000
	global_load_lds_dwordx4 v152, s[2:3]
	s_mov_b32 m0, s68
	s_cmp_lg_u32 s1, 1
	global_load_lds_dwordx4 v148, s[2:3]
	s_cbranch_scc1 .LBB0_289
	s_barrier
	s_setprio 1

; #define PG8_WAIT_V(n) asm volatile("s_waitcnt vmcnt(" #n ")" ::: "memory")
; #define PG8_BAR __builtin_amdgcn_s_barrier()
; template <class Epi>
; __device__ __forceinline__ void gemm_phase(LAS unsigned char* lds, const Gemm g, const Epi& E) {
;     ...
;     PG8_WAIT_V(0);
;     if (wr == 0) PG8_BAR;
;     PG8_BAR;
.LBB0_309:
	s_setprio 0
	v_readlane_b32 s70, v255, 3
	v_readlane_b32 s71, v255, 4
	v_readlane_b32 s92, v255, 8
	v_readlane_b32 s75, v255, 6
	v_readlane_b32 s80, v255, 7
	v_readlane_b32 s93, v255, 9
	s_movk_i32 s71, 0x2000
	s_movk_i32 s36, 0xf000
	s_mov_b64 s[68:69], 0x1000
	v_readlane_b32 s10, v255, 30
	s_barrier

; __device__ __forceinline__ int opaque_tid() { int t = threadIdx.x; asm volatile("" : "+v"(t)); return t; }
; #define PG8_STAGE(bufoff, gbase, voff) do { _Pragma("unroll") for (int _i = 0; _i < 2; ++_i) \
;         __builtin_amdgcn_global_load_lds((const unsigned*)((const char*)(gbase) + (voff)[_i]), (LAS unsigned*)(lds + (bufoff) + ldsw + _i * 8192), 16, 0, 0); } while (0)
; #define PG8_WAIT_V(n) asm volatile("s_waitcnt vmcnt(" #n ")" ::: "memory")
; #define PG8_BAR __builtin_amdgcn_s_barrier()
; template <class Epi>
; __device__ __forceinline__ void gemm_phase(LAS unsigned char* lds, const Gemm g, const Epi& E) {
;     const int tid = opaque_tid(), wid = __builtin_amdgcn_readfirstlane(tid >> 6), lane = tid & 63, wr = wid >> 2, wc = wid & 3, fr = lane & 15, fq = lane >> 4;
;     const int K = g.K, nt = K / BK;
;     StaticOrder S; S.init(g.M, g.N, (int)gridDim.x, (int)blockIdx.x);
;     unsigned voffA[2], voffB[2];
; #pragma unroll
;     for (int i = 0; i < 2; ++i) { int R, C; stage_rc(tid * 16 + i * 8192, R, C); const int Rb = Epi::PERM ? ((R & ~31) + perm32(R & 31)) : R;
;         voffA[i] = (unsigned)(R * g.lda + C) * 2u; voffB[i] = (unsigned)(Rb * g.ldb + C) * 2u; }
;     const size_t kstep = (size_t)(BK * 2);
;     const size_t hstepA = (size_t)HALF * g.lda * 2, hstepB = (size_t)HALF * g.ldb * 2;
;     const size_t tstepA = 2 * hstepA, tstepB = 2 * hstepB;
;     const unsigned ldsw = (unsigned)wid * 1024u;
;     const int aoff = lds_byte(wr * 64 + fr, fq * 8), boff = lds_byte(wc * 32 + fr, fq * 8);
;     ...
;     Unit cur, nxt; int ui = 0;
;     if (!S.next(0, cur)) return;
;     f32x4 acc[2][2][4][2];
; #pragma unroll
;     for (int a = 0; a < 2; ++a)
; #pragma unroll
;         for (int b = 0; b < 2; ++b)
; #pragma unroll
;             for (int m = 0; m < 4; ++m)
; #pragma unroll
;                 for (int n = 0; n < 2; ++n) acc[a][b][m][n] = (f32x4){0.f, 0.f, 0.f, 0.f};
;     bf16x8 At[4][2], B0[2][2], B1[2][2];
;     const char* cA = (const char*)g.A + (size_t)g.mapA.src(cur.pm) * tstepA + (size_t)cur.pn * g.a_pn_step;
;     const char* cB = (const char*)g.Bt + (size_t)g.mapB.src(cur.pn) * tstepB;
;     PG8_STAGE(PG8_SB(0, 0), cB, voffB); PG8_STAGE(PG8_SA(0, 0), cA, voffA); PG8_STAGE(PG8_SB(0, 1), cB + hstepB, voffB); PG8_STAGE(PG8_SA(0, 1), cA + hstepA, voffA);
;     if (wr == 1) PG8_BAR;
;     PG8_WAIT_V(4); PG8_BAR;
.LBB0_321:
	v_readlane_b32 s0, v254, 32
	s_waitcnt vmcnt(2)
	v_mov_b32_e32 v8, v210
	v_readlane_b32 s1, v254, 33
	s_lshl_b32 s68, s4, 4
	s_andn2_b64 vcc, exec, s[0:1]
	v_readfirstlane_b32 s0, v8
	s_cbranch_vccnz .LBB0_369
	v_lshlrev_b32_e32 v1, 4, v8
	v_add_u32_e32 v3, 0x2000, v1
	v_ashrrev_i32_e32 v2, 31, v3
	v_lshrrev_b32_e32 v2, 22, v2
	v_add_u32_e32 v2, v3, v2
	v_ashrrev_i32_e32 v2, 10, v2
	v_mul_i32_i24_e32 v4, 0x400, v2
	v_sub_u32_e32 v3, v3, v4
	v_lshrrev_b32_e32 v4, 4, v3
	v_bitop3_b32 v4, v4, v3, 32 bitop3:0x6c
	v_ashrrev_i32_e32 v3, 31, v4
	v_lshrrev_b32_e32 v3, 26, v3
	v_add_u32_e32 v5, v4, v3
	v_lshlrev_b32_e32 v6, 3, v2
	v_ashrrev_i32_e32 v3, 6, v5
	v_and_b32_e32 v6, -16, v6
	v_add_u32_e32 v6, v3, v6
	v_and_b32_e32 v7, 3, v3
	s_mov_b32 s5, 0x1fffe0
	v_lshrrev_b32_e32 v9, 2, v6
	v_lshlrev_b32_e32 v10, 1, v6
	v_and_b32_e32 v5, 0xc0, v5
	v_and_or_b32 v7, v6, s5, v7
	v_and_b32_e32 v9, 4, v9
	v_and_b32_e32 v10, 24, v10
	v_sub_u32_e32 v4, v4, v5
	v_or3_b32 v7, v7, v9, v10
	v_lshlrev_b32_e32 v9, 5, v2
	v_ashrrev_i16_sdwa v4, v219, sext(v4) dst_sel:DWORD dst_unused:UNUSED_PAD src0_sel:DWORD src1_sel:BYTE_0
	v_and_b32_e32 v9, 32, v9
	v_bfe_i32 v4, v4, 0, 16
	v_add_lshl_u32 v5, v9, v4, 1
	v_lshl_add_u32 v180, v7, 11, v5
	v_lshl_add_u32 v182, v6, 11, v5
	v_bfe_i32 v5, v8, 27, 1
	v_lshrrev_b32_e32 v5, 22, v5
	v_add_u32_e32 v5, v1, v5
	v_and_b32_e32 v5, 0xfffffc00, v5
	v_sub_u32_e32 v1, v1, v5
	v_lshrrev_b32_e32 v5, 4, v1
	v_bitop3_b32 v7, v5, v1, 32 bitop3:0x6c
	v_ashrrev_i32_e32 v1, 31, v1
	v_lshrrev_b32_e32 v1, 26, v1
	v_add_u32_e32 v1, v7, v1
	v_ashrrev_i32_e32 v5, 6, v1
	v_ashrrev_i32_e32 v1, 31, v8
	v_lshrrev_b32_e32 v1, 26, v1
	v_add_u32_e32 v1, v8, v1
	v_ashrrev_i32_e32 v6, 6, v1
	v_lshlrev_b32_e32 v1, 3, v6
	v_and_b32_e32 v1, -16, v1
	v_add_u32_e32 v1, v5, v1
	v_and_b32_e32 v9, 3, v5
	v_lshrrev_b32_e32 v10, 2, v1
	v_lshlrev_b32_e32 v11, 1, v1
	v_and_or_b32 v9, v1, s5, v9
	v_and_b32_e32 v10, 4, v10
	v_and_b32_e32 v11, 24, v11
	s_lshl_b32 s4, s4, 7
	s_ashr_i32 s3, s0, 6
	v_or3_b32 v9, v9, v10, v11
	v_mul_i32_i24_e32 v11, 64, v5
	s_or_b32 s18, s4, 16
	v_readlane_b32 s4, v254, 51
	s_ashr_i32 s2, s0, 8
	s_lshl_b32 s1, s3, 10
	v_sub_u32_e32 v7, v7, v11
	v_readlane_b32 s5, v254, 52
	v_lshlrev_b32_e32 v10, 5, v6
	v_ashrrev_i16_sdwa v7, v219, sext(v7) dst_sel:DWORD dst_unused:UNUSED_PAD src0_sel:DWORD src1_sel:BYTE_0
	s_and_b64 s[4:5], s[4:5], exec
	v_and_b32_e32 v10, 32, v10
	v_bfe_i32 v7, v7, 0, 16
	s_cselect_b32 s4, s68, s18
	v_readlane_b32 s5, v254, 50
	v_add_lshl_u32 v10, v10, v7, 1
	s_add_i32 s4, s4, s5
	s_add_i32 s24, s1, 0
	v_lshl_add_u32 v184, v9, 11, v10
	s_ashr_i32 s5, s4, 31
	s_add_i32 m0, s24, 0x10000
	s_lshl_b64 s[4:5], s[4:5], 19
	global_load_lds_dwordx4 v184, s[8:9]
	s_add_i32 m0, s24, 0x12000
	s_add_u32 s60, s22, s4
	v_lshl_add_u32 v186, v1, 11, v10
	global_load_lds_dwordx4 v180, s[8:9]
	s_addc_u32 s61, s23, s5
	s_mov_b32 m0, s24
	s_add_i32 s25, s24, 0x2000
	global_load_lds_dwordx4 v186, s[60:61]
	s_mov_b32 m0, s25
	s_nop 0
	global_load_lds_dwordx4 v182, s[60:61]
	s_add_i32 m0, s24, 0x14000
	s_nop 0
	global_load_lds_dwordx4 v184, s[26:27]
	s_add_i32 m0, s24, 0x16000
	s_add_u32 s4, s60, 0x40000
	s_addc_u32 s5, s61, 0
	s_add_i32 s31, s24, 0x4000
	global_load_lds_dwordx4 v180, s[26:27]
	s_mov_b32 m0, s31
	s_add_i32 s36, s24, 0x6000
	global_load_lds_dwordx4 v186, s[4:5]
	s_mov_b32 m0, s36
	s_cmp_lg_u32 s2, 1
	global_load_lds_dwordx4 v182, s[4:5]
	s_cbranch_scc1 .LBB0_324
	s_barrier
	s_setprio 1

; #define PG8_WAIT_V(n) asm volatile("s_waitcnt vmcnt(" #n ")" ::: "memory")
; #define PG8_BAR __builtin_amdgcn_s_barrier()
; template <class Epi>
; __device__ __forceinline__ void gemm_phase(LAS unsigned char* lds, const Gemm g, const Epi& E) {
;     ...
;     PG8_WAIT_V(0);
;     if (wr == 0) PG8_BAR;
;     PG8_BAR;
.LBB0_368:
	s_setprio 0
	s_barrier

; __device__ __forceinline__ int opaque_tid() { int t = threadIdx.x; asm volatile("" : "+v"(t)); return t; }
; #define PG8_STAGE(bufoff, gbase, voff) do { _Pragma("unroll") for (int _i = 0; _i < 2; ++_i) \
;         __builtin_amdgcn_global_load_lds((const unsigned*)((const char*)(gbase) + (voff)[_i]), (LAS unsigned*)(lds + (bufoff) + ldsw + _i * 8192), 16, 0, 0); } while (0)
; #define PG8_WAIT_V(n) asm volatile("s_waitcnt vmcnt(" #n ")" ::: "memory")
; #define PG8_BAR __builtin_amdgcn_s_barrier()
; template <class Epi>
; __device__ __forceinline__ void gemm_phase(LAS unsigned char* lds, const Gemm g, const Epi& E) {
;     const int tid = opaque_tid(), wid = __builtin_amdgcn_readfirstlane(tid >> 6), lane = tid & 63, wr = wid >> 2, wc = wid & 3, fr = lane & 15, fq = lane >> 4;
;     const int K = g.K, nt = K / BK;
;     StaticOrder S; S.init(g.M, g.N, (int)gridDim.x, (int)blockIdx.x);
;     unsigned voffA[2], voffB[2];
; #pragma unroll
;     for (int i = 0; i < 2; ++i) { int R, C; stage_rc(tid * 16 + i * 8192, R, C); const int Rb = Epi::PERM ? ((R & ~31) + perm32(R & 31)) : R;
;         voffA[i] = (unsigned)(R * g.lda + C) * 2u; voffB[i] = (unsigned)(Rb * g.ldb + C) * 2u; }
;     const size_t kstep = (size_t)(BK * 2);
;     const size_t hstepA = (size_t)HALF * g.lda * 2, hstepB = (size_t)HALF * g.ldb * 2;
;     const size_t tstepA = 2 * hstepA, tstepB = 2 * hstepB;
;     const unsigned ldsw = (unsigned)wid * 1024u;
;     const int aoff = lds_byte(wr * 64 + fr, fq * 8), boff = lds_byte(wc * 32 + fr, fq * 8);
;     ...
;     Unit cur, nxt; int ui = 0;
;     if (!S.next(0, cur)) return;
;     f32x4 acc[2][2][4][2];
; #pragma unroll
;     for (int a = 0; a < 2; ++a)
; #pragma unroll
;         for (int b = 0; b < 2; ++b)
; #pragma unroll
;             for (int m = 0; m < 4; ++m)
; #pragma unroll
;                 for (int n = 0; n < 2; ++n) acc[a][b][m][n] = (f32x4){0.f, 0.f, 0.f, 0.f};
;     bf16x8 At[4][2], B0[2][2], B1[2][2];
;     const char* cA = (const char*)g.A + (size_t)g.mapA.src(cur.pm) * tstepA + (size_t)cur.pn * g.a_pn_step;
;     const char* cB = (const char*)g.Bt + (size_t)g.mapB.src(cur.pn) * tstepB;
;     PG8_STAGE(PG8_SB(0, 0), cB, voffB); PG8_STAGE(PG8_SA(0, 0), cA, voffA); PG8_STAGE(PG8_SB(0, 1), cB + hstepB, voffB); PG8_STAGE(PG8_SA(0, 1), cA + hstepA, voffA);
;     if (wr == 1) PG8_BAR;
;     PG8_WAIT_V(4); PG8_BAR;
.LBB0_466:
	s_or_b64 exec, exec, s[2:3]
	s_waitcnt vmcnt(2)
	v_mov_b32_e32 v10, v210
	s_lshr_b32 s30, s1, 8
	s_lshr_b32 s76, s1, 5
	s_barrier
	s_cmp_ge_i32 s37, s76
	v_readfirstlane_b32 s1, v10
	s_cbranch_scc1 .LBB0_480
	v_lshlrev_b32_e32 v1, 4, v10
	v_add_u32_e32 v2, 0x2000, v1
	v_ashrrev_i32_e32 v3, 31, v2
	v_lshrrev_b32_e32 v3, 22, v3
	v_add_u32_e32 v3, v2, v3
	v_ashrrev_i32_e32 v11, 10, v3
	v_mul_i32_i24_e32 v3, 0x400, v11
	v_sub_u32_e32 v2, v2, v3
	v_lshrrev_b32_e32 v3, 4, v2
	v_bitop3_b32 v2, v3, v2, 32 bitop3:0x6c
	v_ashrrev_i32_e32 v3, 31, v2
	v_lshrrev_b32_e32 v3, 26, v3
	v_add_u32_e32 v3, v2, v3
	v_lshlrev_b32_e32 v4, 3, v11
	v_ashrrev_i32_e32 v12, 6, v3
	v_and_b32_e32 v4, -16, v4
	v_add_u32_e32 v4, v12, v4
	v_and_b32_e32 v5, 3, v12
	s_mov_b32 s4, 0x1fffe0
	v_lshrrev_b32_e32 v6, 2, v4
	v_lshlrev_b32_e32 v7, 1, v4
	v_and_b32_e32 v3, 0xc0, v3
	v_and_or_b32 v5, v4, s4, v5
	v_and_b32_e32 v6, 4, v6
	v_and_b32_e32 v7, 24, v7
	v_sub_u32_e32 v2, v2, v3
	v_or3_b32 v5, v5, v6, v7
	v_lshlrev_b32_e32 v6, 5, v11
	v_ashrrev_i16_sdwa v2, v219, sext(v2) dst_sel:DWORD dst_unused:UNUSED_PAD src0_sel:DWORD src1_sel:BYTE_0
	v_and_b32_e32 v6, 32, v6
	v_bfe_i32 v13, v2, 0, 16
	v_add_lshl_u32 v2, v6, v13, 1
	v_lshl_add_u32 v166, v5, 11, v2
	v_lshl_add_u32 v168, v4, 11, v2
	v_bfe_i32 v2, v10, 27, 1
	v_lshrrev_b32_e32 v2, 22, v2
	v_add_u32_e32 v2, v1, v2
	v_and_b32_e32 v2, 0xfffffc00, v2
	v_sub_u32_e32 v1, v1, v2
	v_lshrrev_b32_e32 v2, 4, v1
	v_bitop3_b32 v2, v2, v1, 32 bitop3:0x6c
	v_ashrrev_i32_e32 v1, 31, v1
	v_lshrrev_b32_e32 v1, 26, v1
	v_add_u32_e32 v1, v2, v1
	v_ashrrev_i32_e32 v14, 6, v1
	v_ashrrev_i32_e32 v1, 31, v10
	v_lshrrev_b32_e32 v1, 26, v1
	v_add_u32_e32 v1, v10, v1
	v_ashrrev_i32_e32 v15, 6, v1
	v_lshlrev_b32_e32 v1, 3, v15
	v_and_b32_e32 v1, -16, v1
	v_add_u32_e32 v1, v14, v1
	v_and_b32_e32 v3, 3, v14
	s_ashr_i32 s2, s1, 6
	v_and_or_b32 v3, v1, s4, v3
	v_readlane_b32 s4, v254, 46
	s_ashr_i32 s3, s1, 8
	s_lshl_b32 s18, s2, 10
	s_or_b32 s24, s30, 1
	v_readlane_b32 s5, v254, 47
	s_and_b64 s[4:5], s[4:5], exec
	s_cselect_b32 s4, s24, s30
	s_mul_i32 s4, s4, s80
	s_add_i32 s4, s4, s75
	s_ashr_i32 s5, s4, 31
	s_lshr_b32 s5, s5, 27
	s_add_i32 s5, s4, s5
	v_lshrrev_b32_e32 v4, 2, v1
	v_lshlrev_b32_e32 v5, 1, v1
	s_ashr_i32 s6, s5, 5
	v_and_b32_e32 v4, 4, v4
	v_and_b32_e32 v5, 24, v5
	s_lshl_b32 s6, s6, 2
	v_or3_b32 v3, v3, v4, v5
	v_mul_i32_i24_e32 v5, 64, v14
	s_sub_i32 s7, s30, s6
	v_sub_u32_e32 v2, v2, v5
	s_min_i32 s7, s7, 4
	v_ashrrev_i16_sdwa v2, v219, sext(v2) dst_sel:DWORD dst_unused:UNUSED_PAD src0_sel:DWORD src1_sel:BYTE_0
	s_abs_i32 s8, s7
	s_waitcnt vmcnt(1)
	v_bfe_i32 v16, v2, 0, 16
	v_cvt_f32_u32_e32 v2, s8
	v_lshlrev_b32_e32 v4, 5, v15
	v_and_b32_e32 v4, 32, v4
	v_add_lshl_u32 v4, v4, v16, 1
	v_lshl_add_u32 v172, v1, 11, v4
	v_rcp_iflag_f32_e32 v1, v2
	s_sub_i32 s10, 0, s8
	s_andn2_b32 s5, s5, 31
	s_sub_i32 s4, s4, s5
	v_mul_f32_e32 v1, 0x4f7ffffe, v1
	v_cvt_u32_f32_e32 v1, v1
	s_abs_i32 s9, s4
	s_xor_b32 s5, s4, s7
	s_ashr_i32 s5, s5, 31
	v_readfirstlane_b32 s11, v1
	s_mul_i32 s10, s10, s11
	s_mul_hi_u32 s10, s11, s10
	s_add_i32 s11, s11, s10
	s_mul_hi_u32 s10, s9, s11
	s_mul_i32 s11, s10, s8
	s_sub_i32 s9, s9, s11
	s_add_i32 s11, s10, 1
	s_sub_i32 s12, s9, s8
	s_cmp_ge_u32 s9, s8
	s_cselect_b32 s10, s11, s10
	s_cselect_b32 s9, s12, s9
	s_add_i32 s11, s10, 1
	s_cmp_ge_u32 s9, s8
	s_cselect_b32 s8, s11, s10
	s_xor_b32 s8, s8, s5
	s_sub_i32 s12, s8, s5
	s_mul_i32 s5, s12, s7
	s_sub_i32 s4, s4, s5
	s_add_i32 s52, s6, s4
	v_readlane_b32 s4, v255, 23
	v_readlane_b32 s5, v255, 24
	s_and_b64 s[4:5], s[4:5], exec
	v_readlane_b32 s4, v255, 27
	s_cselect_b32 s25, 32, -2.0
	s_cmp_ge_i32 s52, s4
	s_cselect_b32 s4, s25, 0
	s_add_i32 s4, s4, s52
	s_ashr_i32 s5, s4, 31
	s_ashr_i32 s13, s12, 31
	s_lshl_b64 s[4:5], s[4:5], 19
	s_lshl_b64 s[6:7], s[12:13], 19
	v_readlane_b32 s8, v255, 28
	s_add_u32 s16, s8, s6
	v_readlane_b32 s6, v255, 29
	s_addc_u32 s17, s6, s7
	s_add_i32 s13, s18, 0
	v_lshl_add_u32 v170, v3, 11, v4
	s_add_i32 m0, s13, 0x10000
	v_mov_b32_e32 v171, v0
	global_load_lds_dwordx4 v170, s[16:17]
	s_add_i32 m0, s13, 0x12000
	s_add_u32 s14, s22, s4
	global_load_lds_dwordx4 v166, s[16:17]
	s_addc_u32 s15, s23, s5
	s_mov_b32 m0, s13
	s_add_i32 s31, s13, 0x2000
	global_load_lds_dwordx4 v172, s[14:15]
	s_mov_b32 m0, s31
	s_add_u32 s4, s16, 0x40000
	global_load_lds_dwordx4 v168, s[14:15]
	s_addc_u32 s5, s17, 0
	s_add_i32 m0, s13, 0x14000
	v_mov_b32_e32 v167, v0
	global_load_lds_dwordx4 v170, s[4:5]
	s_add_i32 m0, s13, 0x16000
	v_mov_b32_e32 v173, v0
	global_load_lds_dwordx4 v166, s[4:5]
	s_add_u32 s4, s14, 0x40000
	s_addc_u32 s5, s15, 0
	s_add_i32 s36, s13, 0x4000
	s_mov_b32 m0, s36
	s_add_i32 s44, s13, 0x6000
	global_load_lds_dwordx4 v172, s[4:5]
	s_mov_b32 m0, s44
	v_mov_b32_e32 v169, v0
	global_load_lds_dwordx4 v168, s[4:5]
	v_lshl_add_u64 v[8:9], s[16:17], 0, v[170:171]
	v_lshl_add_u64 v[6:7], s[16:17], 0, v[166:167]
	v_lshl_add_u64 v[4:5], s[14:15], 0, v[172:173]
	s_cmp_lg_u32 s3, 1
	v_lshl_add_u64 v[2:3], s[14:15], 0, v[168:169]
	s_cbranch_scc1 .LBB0_469
	s_barrier
	s_setprio 1

; #define PG8_WAIT_V(n) asm volatile("s_waitcnt vmcnt(" #n ")" ::: "memory")
; #define PG8_BAR __builtin_amdgcn_s_barrier()
; template <class Epi>
; __device__ __forceinline__ void gemm_phase(LAS unsigned char* lds, const Gemm g, const Epi& E) {
;     ...
;     PG8_WAIT_V(0);
;     if (wr == 0) PG8_BAR;
;     PG8_BAR;
.LBB0_479:
	s_setprio 0
	s_movk_i32 s36, 0xf000
	s_barrier

; __device__ __forceinline__ int opaque_tid() { int t = threadIdx.x; asm volatile("" : "+v"(t)); return t; }
; #define PG8_STAGE(bufoff, gbase, voff) do { _Pragma("unroll") for (int _i = 0; _i < 2; ++_i) \
;         __builtin_amdgcn_global_load_lds((const unsigned*)((const char*)(gbase) + (voff)[_i]), (LAS unsigned*)(lds + (bufoff) + ldsw + _i * 8192), 16, 0, 0); } while (0)
; #define PG8_WAIT_V(n) asm volatile("s_waitcnt vmcnt(" #n ")" ::: "memory")
; #define PG8_BAR __builtin_amdgcn_s_barrier()
; template <class Epi>
; __device__ __forceinline__ void gemm_phase(LAS unsigned char* lds, const Gemm g, const Epi& E) {
;     const int tid = opaque_tid(), wid = __builtin_amdgcn_readfirstlane(tid >> 6), lane = tid & 63, wr = wid >> 2, wc = wid & 3, fr = lane & 15, fq = lane >> 4;
;     const int K = g.K, nt = K / BK;
;     StaticOrder S; S.init(g.M, g.N, (int)gridDim.x, (int)blockIdx.x);
;     unsigned voffA[2], voffB[2];
; #pragma unroll
;     for (int i = 0; i < 2; ++i) { int R, C; stage_rc(tid * 16 + i * 8192, R, C); const int Rb = Epi::PERM ? ((R & ~31) + perm32(R & 31)) : R;
;         voffA[i] = (unsigned)(R * g.lda + C) * 2u; voffB[i] = (unsigned)(Rb * g.ldb + C) * 2u; }
;     const size_t kstep = (size_t)(BK * 2);
;     const size_t hstepA = (size_t)HALF * g.lda * 2, hstepB = (size_t)HALF * g.ldb * 2;
;     const size_t tstepA = 2 * hstepA, tstepB = 2 * hstepB;
;     const unsigned ldsw = (unsigned)wid * 1024u;
;     const int aoff = lds_byte(wr * 64 + fr, fq * 8), boff = lds_byte(wc * 32 + fr, fq * 8);
;     ...
;     Unit cur, nxt; int ui = 0;
;     if (!S.next(0, cur)) return;
;     f32x4 acc[2][2][4][2];
; #pragma unroll
;     for (int a = 0; a < 2; ++a)
; #pragma unroll
;         for (int b = 0; b < 2; ++b)
; #pragma unroll
;             for (int m = 0; m < 4; ++m)
; #pragma unroll
;                 for (int n = 0; n < 2; ++n) acc[a][b][m][n] = (f32x4){0.f, 0.f, 0.f, 0.f};
;     bf16x8 At[4][2], B0[2][2], B1[2][2];
;     const char* cA = (const char*)g.A + (size_t)g.mapA.src(cur.pm) * tstepA + (size_t)cur.pn * g.a_pn_step;
;     const char* cB = (const char*)g.Bt + (size_t)g.mapB.src(cur.pn) * tstepB;
;     PG8_STAGE(PG8_SB(0, 0), cB, voffB); PG8_STAGE(PG8_SA(0, 0), cA, voffA); PG8_STAGE(PG8_SB(0, 1), cB + hstepB, voffB); PG8_STAGE(PG8_SA(0, 1), cA + hstepA, voffA);
;     if (wr == 1) PG8_BAR;
;     PG8_WAIT_V(4); PG8_BAR;
.LBB0_486:
	s_or_b64 exec, exec, s[2:3]
	v_mov_b32_e32 v8, v210
	s_lshr_b32 s76, s1, 6
	s_barrier
	s_cmp_ge_i32 s37, s76
	v_readfirstlane_b32 s1, v8
	s_cbranch_scc1 .LBB0_500
	v_lshlrev_b32_e32 v1, 4, v8
	v_add_u32_e32 v3, 0x2000, v1
	v_ashrrev_i32_e32 v2, 31, v3
	v_lshrrev_b32_e32 v2, 22, v2
	v_add_u32_e32 v2, v3, v2
	v_ashrrev_i32_e32 v2, 10, v2
	v_lshlrev_b32_e32 v4, 5, v2
	v_and_b32_e32 v5, 32, v4
	v_mul_i32_i24_e32 v4, 0x400, v2
	v_sub_u32_e32 v3, v3, v4
	v_lshrrev_b32_e32 v4, 4, v3
	v_bitop3_b32 v4, v4, v3, 32 bitop3:0x6c
	v_ashrrev_i32_e32 v3, 31, v4
	v_lshrrev_b32_e32 v3, 26, v3
	v_add_u32_e32 v6, v4, v3
	v_ashrrev_i32_e32 v3, 6, v6
	v_and_b32_e32 v6, 0xc0, v6
	v_sub_u32_e32 v4, v4, v6
	v_ashrrev_i16_sdwa v4, v219, sext(v4) dst_sel:DWORD dst_unused:UNUSED_PAD src0_sel:DWORD src1_sel:BYTE_0
	v_lshlrev_b32_e32 v6, 3, v2
	v_bfe_i32 v4, v4, 0, 16
	v_and_b32_e32 v6, 0xffff0, v6
	v_add_u32_e32 v5, v5, v4
	v_add_lshl_u32 v6, v3, v6, 12
	v_lshl_add_u32 v146, v5, 1, v6
	v_ashrrev_i32_e32 v5, 31, v8
	v_lshrrev_b32_e32 v5, 26, v5
	v_add_u32_e32 v5, v8, v5
	v_ashrrev_i32_e32 v5, 6, v5
	v_lshlrev_b32_e32 v6, 5, v5
	v_and_b32_e32 v9, 32, v6
	v_bfe_i32 v6, v8, 27, 1
	v_readlane_b32 s2, v255, 21
	v_lshrrev_b32_e32 v6, 22, v6
	v_readlane_b32 s3, v255, 22
	v_add_u32_e32 v6, v1, v6
	s_lshl_b64 s[2:3], s[2:3], 22
	v_readlane_b32 s4, v254, 40
	v_and_b32_e32 v6, 0xfffffc00, v6
	s_add_u32 s18, s4, s2
	v_readlane_b32 s2, v254, 41
	v_sub_u32_e32 v1, v1, v6
	v_readlane_b32 s4, v255, 26
	s_addc_u32 s24, s2, s3
	v_lshrrev_b32_e32 v6, 4, v1
	s_lshr_b32 s28, s4, 9
	v_readlane_b32 s4, v254, 49
	v_bitop3_b32 v7, v6, v1, 32 bitop3:0x6c
	v_ashrrev_i32_e32 v1, 31, v1
	s_or_b32 s4, s28, s4
	v_lshrrev_b32_e32 v1, 26, v1
	s_mul_i32 s4, s4, s80
	v_add_u32_e32 v1, v7, v1
	s_add_i32 s4, s4, s75
	v_ashrrev_i32_e32 v6, 6, v1
	s_ashr_i32 s5, s4, 31
	v_mul_i32_i24_e32 v1, 64, v6
	s_lshr_b32 s5, s5, 28
	v_sub_u32_e32 v1, v7, v1
	s_add_i32 s5, s4, s5
	v_ashrrev_i16_sdwa v1, v219, sext(v1) dst_sel:DWORD dst_unused:UNUSED_PAD src0_sel:DWORD src1_sel:BYTE_0
	s_ashr_i32 s6, s5, 4
	v_bfe_i32 v7, v1, 0, 16
	s_lshl_b32 s6, s6, 2
	v_add_u32_e32 v1, v9, v7
	v_lshlrev_b32_e32 v9, 3, v5
	s_sub_i32 s7, s30, s6
	v_and_b32_e32 v9, 0xffff0, v9
	s_min_i32 s7, s7, 4
	v_add_lshl_u32 v9, v6, v9, 12
	s_abs_i32 s9, s7
	v_lshl_add_u32 v148, v1, 1, v9
	v_cvt_f32_u32_e32 v1, s9
	s_sub_i32 s10, 0, s9
	s_and_b32 s5, s5, -16
	s_sub_i32 s4, s4, s5
	v_rcp_iflag_f32_e32 v1, v1
	s_abs_i32 s8, s4
	s_ashr_i32 s2, s1, 6
	s_xor_b32 s5, s4, s7
	v_mul_f32_e32 v1, 0x4f7ffffe, v1
	v_cvt_u32_f32_e32 v1, v1
	s_ashr_i32 s3, s1, 8
	s_lshl_b32 s25, s2, 10
	s_ashr_i32 s5, s5, 31
	v_readfirstlane_b32 s11, v1
	s_mul_i32 s10, s10, s11
	s_mul_hi_u32 s10, s11, s10
	s_add_i32 s11, s11, s10
	s_mul_hi_u32 s10, s8, s11
	s_mul_i32 s11, s10, s9
	s_sub_i32 s8, s8, s11
	s_add_i32 s11, s10, 1
	s_sub_i32 s12, s8, s9
	s_cmp_ge_u32 s8, s9
	s_cselect_b32 s10, s11, s10
	s_cselect_b32 s8, s12, s8
	s_add_i32 s11, s10, 1
	s_cmp_ge_u32 s8, s9
	s_cselect_b32 s8, s11, s10
	s_xor_b32 s8, s8, s5
	s_sub_i32 s10, s8, s5
	s_mul_i32 s5, s10, s7
	s_sub_i32 s4, s4, s5
	s_add_i32 s61, s6, s4
	v_readlane_b32 s4, v255, 23
	v_readlane_b32 s5, v255, 24
	s_and_b64 s[4:5], s[4:5], exec
	v_readlane_b32 s4, v255, 27
	s_cselect_b32 s29, 32, -2.0
	s_cmp_ge_i32 s61, s4
	s_cselect_b32 s4, s29, 0
	s_add_i32 s4, s4, s61
	s_ashr_i32 s5, s4, 31
	s_ashr_i32 s11, s10, 31
	s_lshl_b64 s[4:5], s[4:5], 20
	s_lshl_b64 s[6:7], s[10:11], 20
	s_add_u32 s14, s18, s6
	s_addc_u32 s15, s24, s7
	s_add_i32 s11, s25, 0
	s_add_i32 m0, s11, 0x10000
	s_nop 0
	global_load_lds_dwordx4 v148, s[14:15]
	s_add_i32 m0, s11, 0x12000
	s_add_u32 s12, s34, s4
	global_load_lds_dwordx4 v146, s[14:15]
	s_addc_u32 s13, s35, s5
	s_mov_b32 m0, s11
	s_add_i32 s31, s11, 0x2000
	global_load_lds_dwordx4 v148, s[12:13]
	s_mov_b32 m0, s31
	s_add_u32 s4, s14, 0x80000
	global_load_lds_dwordx4 v146, s[12:13]
	s_addc_u32 s5, s15, 0
	s_add_i32 m0, s11, 0x14000
	s_nop 0
	global_load_lds_dwordx4 v148, s[4:5]
	s_add_i32 m0, s11, 0x16000
	s_nop 0
	global_load_lds_dwordx4 v146, s[4:5]
	s_add_u32 s4, s12, 0x80000
	s_addc_u32 s5, s13, 0
	s_add_i32 s36, s11, 0x4000
	s_mov_b32 m0, s36
	s_add_i32 s44, s11, 0x6000
	global_load_lds_dwordx4 v148, s[4:5]
	s_mov_b32 m0, s44
	s_cmp_lg_u32 s3, 1
	global_load_lds_dwordx4 v146, s[4:5]
	s_cbranch_scc1 .LBB0_489
	s_barrier
	s_setprio 1

; __device__ __forceinline__ int opaque_tid() { int t = threadIdx.x; asm volatile("" : "+v"(t)); return t; }
; #define PG8_STAGE(bufoff, gbase, voff) do { _Pragma("unroll") for (int _i = 0; _i < 2; ++_i) \
;         __builtin_amdgcn_global_load_lds((const unsigned*)((const char*)(gbase) + (voff)[_i]), (LAS unsigned*)(lds + (bufoff) + ldsw + _i * 8192), 16, 0, 0); } while (0)
; #define PG8_WAIT_V(n) asm volatile("s_waitcnt vmcnt(" #n ")" ::: "memory")
; #define PG8_BAR __builtin_amdgcn_s_barrier()
; template <class Epi>
; __device__ __forceinline__ void gemm_phase(LAS unsigned char* lds, const Gemm g, const Epi& E) {
;     const int tid = opaque_tid(), wid = __builtin_amdgcn_readfirstlane(tid >> 6), lane = tid & 63, wr = wid >> 2, wc = wid & 3, fr = lane & 15, fq = lane >> 4;
;     const int K = g.K, nt = K / BK;
;     StaticOrder S; S.init(g.M, g.N, (int)gridDim.x, (int)blockIdx.x);
;     unsigned voffA[2], voffB[2];
; #pragma unroll
;     for (int i = 0; i < 2; ++i) { int R, C; stage_rc(tid * 16 + i * 8192, R, C); const int Rb = Epi::PERM ? ((R & ~31) + perm32(R & 31)) : R;
;         voffA[i] = (unsigned)(R * g.lda + C) * 2u; voffB[i] = (unsigned)(Rb * g.ldb + C) * 2u; }
;     const size_t kstep = (size_t)(BK * 2);
;     const size_t hstepA = (size_t)HALF * g.lda * 2, hstepB = (size_t)HALF * g.ldb * 2;
;     const size_t tstepA = 2 * hstepA, tstepB = 2 * hstepB;
;     const unsigned ldsw = (unsigned)wid * 1024u;
;     const int aoff = lds_byte(wr * 64 + fr, fq * 8), boff = lds_byte(wc * 32 + fr, fq * 8);
;     ...
;     Unit cur, nxt; int ui = 0;
;     if (!S.next(0, cur)) return;
;     f32x4 acc[2][2][4][2];
; #pragma unroll
;     for (int a = 0; a < 2; ++a)
; #pragma unroll
;         for (int b = 0; b < 2; ++b)
; #pragma unroll
;             for (int m = 0; m < 4; ++m)
; #pragma unroll
;                 for (int n = 0; n < 2; ++n) acc[a][b][m][n] = (f32x4){0.f, 0.f, 0.f, 0.f};
;     bf16x8 At[4][2], B0[2][2], B1[2][2];
;     const char* cA = (const char*)g.A + (size_t)g.mapA.src(cur.pm) * tstepA + (size_t)cur.pn * g.a_pn_step;
;     const char* cB = (const char*)g.Bt + (size_t)g.mapB.src(cur.pn) * tstepB;
;     PG8_STAGE(PG8_SB(0, 0), cB, voffB); PG8_STAGE(PG8_SA(0, 0), cA, voffA); PG8_STAGE(PG8_SB(0, 1), cB + hstepB, voffB); PG8_STAGE(PG8_SA(0, 1), cA + hstepA, voffA);
;     if (wr == 1) PG8_BAR;
;     PG8_WAIT_V(4); PG8_BAR;
.LBB0_516:
	s_or_b64 exec, exec, s[2:3]
	s_lshr_b32 s28, s1, 8
	v_mov_b32_e32 v8, v210
	s_mul_i32 s76, s28, 22
	s_barrier
	s_cmp_ge_i32 s37, s76
	v_readfirstlane_b32 s1, v8
	s_cbranch_scc1 .LBB0_530
	v_lshlrev_b32_e32 v1, 4, v8
	v_add_u32_e32 v3, 0x2000, v1
	v_ashrrev_i32_e32 v2, 31, v3
	v_lshrrev_b32_e32 v2, 22, v2
	v_add_u32_e32 v2, v3, v2
	v_ashrrev_i32_e32 v2, 10, v2
	v_mul_i32_i24_e32 v4, 0x400, v2
	v_sub_u32_e32 v3, v3, v4
	v_lshrrev_b32_e32 v4, 4, v3
	v_bitop3_b32 v4, v4, v3, 32 bitop3:0x6c
	v_ashrrev_i32_e32 v3, 31, v4
	v_lshrrev_b32_e32 v3, 26, v3
	v_add_u32_e32 v5, v4, v3
	v_lshlrev_b32_e32 v6, 3, v2
	v_readlane_b32 s3, v255, 20
	v_ashrrev_i32_e32 v3, 6, v5
	v_and_b32_e32 v6, -16, v6
	s_mul_hi_u32 s2, s3, 0xb00000
	s_mul_i32 s3, s3, 0xb00000
	v_readlane_b32 s4, v254, 42
	v_add_u32_e32 v6, v3, v6
	s_add_u32 s18, s4, s3
	v_and_b32_e32 v7, 3, v3
	s_mov_b32 s4, 0x1fffe0
	v_lshrrev_b32_e32 v9, 2, v6
	v_lshlrev_b32_e32 v10, 1, v6
	v_and_b32_e32 v5, 0xc0, v5
	v_and_or_b32 v7, v6, s4, v7
	v_and_b32_e32 v9, 4, v9
	v_and_b32_e32 v10, 24, v10
	v_sub_u32_e32 v4, v4, v5
	v_or3_b32 v7, v7, v9, v10
	v_lshlrev_b32_e32 v9, 5, v2
	v_ashrrev_i16_sdwa v4, v219, sext(v4) dst_sel:DWORD dst_unused:UNUSED_PAD src0_sel:DWORD src1_sel:BYTE_0
	v_and_b32_e32 v9, 32, v9
	v_bfe_i32 v4, v4, 0, 16
	v_add_lshl_u32 v5, v9, v4, 1
	v_lshl_add_u32 v130, v7, 11, v5
	v_lshl_add_u32 v132, v6, 11, v5
	v_bfe_i32 v5, v8, 27, 1
	v_lshrrev_b32_e32 v5, 22, v5
	v_add_u32_e32 v5, v1, v5
	v_and_b32_e32 v5, 0xfffffc00, v5
	v_sub_u32_e32 v1, v1, v5
	v_lshrrev_b32_e32 v5, 4, v1
	v_bitop3_b32 v7, v5, v1, 32 bitop3:0x6c
	v_ashrrev_i32_e32 v1, 31, v1
	v_lshrrev_b32_e32 v1, 26, v1
	v_add_u32_e32 v1, v7, v1
	v_ashrrev_i32_e32 v5, 6, v1
	v_ashrrev_i32_e32 v1, 31, v8
	v_lshrrev_b32_e32 v1, 26, v1
	v_add_u32_e32 v1, v8, v1
	v_ashrrev_i32_e32 v6, 6, v1
	v_lshlrev_b32_e32 v1, 3, v6
	v_and_b32_e32 v1, -16, v1
	v_readlane_b32 s3, v254, 43
	v_add_u32_e32 v1, v5, v1
	v_and_b32_e32 v9, 3, v5
	s_addc_u32 s24, s3, s2
	s_ashr_i32 s2, s1, 6
	v_and_or_b32 v9, v1, s4, v9
	s_lshr_b32 s29, s76, 3
	v_readlane_b32 s4, v254, 46
	s_ashr_i32 s3, s1, 8
	s_lshl_b32 s25, s2, 10
	s_or_b32 s30, s29, 1
	v_readlane_b32 s5, v254, 47
	s_and_b64 s[4:5], s[4:5], exec
	s_cselect_b32 s4, s30, s29
	s_mul_i32 s4, s4, s80
	s_add_i32 s4, s4, s75
	s_mul_hi_i32 s5, s4, 0x2e8ba2e9
	s_lshr_b32 s6, s5, 31
	s_ashr_i32 s5, s5, 4
	s_add_i32 s5, s5, s6
	s_lshl_b32 s6, s5, 2
	v_lshrrev_b32_e32 v10, 2, v1
	v_lshlrev_b32_e32 v11, 1, v1
	s_sub_i32 s7, s28, s6
	v_and_b32_e32 v10, 4, v10
	v_and_b32_e32 v11, 24, v11
	s_min_i32 s7, s7, 4
	v_or3_b32 v9, v9, v10, v11
	v_mul_i32_i24_e32 v11, 64, v5
	s_abs_i32 s8, s7
	v_sub_u32_e32 v7, v7, v11
	v_cvt_f32_u32_e32 v11, s8
	v_lshlrev_b32_e32 v10, 5, v6
	v_ashrrev_i16_sdwa v7, v219, sext(v7) dst_sel:DWORD dst_unused:UNUSED_PAD src0_sel:DWORD src1_sel:BYTE_0
	v_and_b32_e32 v10, 32, v10
	v_bfe_i32 v7, v7, 0, 16
	v_add_lshl_u32 v10, v10, v7, 1
	v_lshl_add_u32 v136, v1, 11, v10
	v_rcp_iflag_f32_e32 v1, v11
	s_sub_i32 s10, 0, s8
	s_mulk_i32 s5, 0x58
	s_sub_i32 s4, s4, s5
	v_mul_f32_e32 v1, 0x4f7ffffe, v1
	v_cvt_u32_f32_e32 v1, v1
	s_abs_i32 s9, s4
	s_xor_b32 s5, s4, s7
	s_ashr_i32 s5, s5, 31
	v_readfirstlane_b32 s11, v1
	s_mul_i32 s10, s10, s11
	s_mul_hi_u32 s10, s11, s10
	s_add_i32 s11, s11, s10
	s_mul_hi_u32 s10, s9, s11
	s_mul_i32 s11, s10, s8
	s_sub_i32 s9, s9, s11
	s_add_i32 s11, s10, 1
	s_sub_i32 s12, s9, s8
	s_cmp_ge_u32 s9, s8
	s_cselect_b32 s10, s11, s10
	s_cselect_b32 s9, s12, s9
	s_add_i32 s11, s10, 1
	s_cmp_ge_u32 s9, s8
	s_cselect_b32 s8, s11, s10
	s_xor_b32 s8, s8, s5
	s_sub_i32 s10, s8, s5
	s_mul_i32 s5, s10, s7
	s_sub_i32 s4, s4, s5
	s_add_i32 s64, s6, s4
	v_readlane_b32 s4, v255, 23
	v_readlane_b32 s5, v255, 24
	s_and_b64 s[4:5], s[4:5], exec
	v_readlane_b32 s4, v255, 27
	s_cselect_b32 s31, 32, -2.0
	s_cmp_ge_i32 s64, s4
	s_cselect_b32 s4, s31, 0
	s_add_i32 s4, s4, s64
	s_ashr_i32 s5, s4, 31
	s_ashr_i32 s11, s10, 31
	s_lshl_b64 s[4:5], s[4:5], 19
	s_lshl_b64 s[6:7], s[10:11], 19
	s_add_u32 s14, s18, s6
	s_addc_u32 s15, s24, s7
	s_add_i32 s11, s25, 0
	v_lshl_add_u32 v134, v9, 11, v10
	s_add_i32 m0, s11, 0x10000
	s_nop 0
	global_load_lds_dwordx4 v134, s[14:15]
	s_add_i32 m0, s11, 0x12000
	s_add_u32 s12, s22, s4
	global_load_lds_dwordx4 v130, s[14:15]
	s_addc_u32 s13, s23, s5
	s_mov_b32 m0, s11
	s_add_i32 s36, s11, 0x2000
	global_load_lds_dwordx4 v136, s[12:13]
	s_mov_b32 m0, s36
	s_add_u32 s4, s14, 0x40000
	global_load_lds_dwordx4 v132, s[12:13]
	s_addc_u32 s5, s15, 0
	s_add_i32 m0, s11, 0x14000
	s_nop 0
	global_load_lds_dwordx4 v134, s[4:5]
	s_add_i32 m0, s11, 0x16000
	s_nop 0
	global_load_lds_dwordx4 v130, s[4:5]
	s_add_u32 s4, s12, 0x40000
	s_addc_u32 s5, s13, 0
	s_add_i32 s44, s11, 0x4000
	s_mov_b32 m0, s44
	s_add_i32 s50, s11, 0x6000
	global_load_lds_dwordx4 v136, s[4:5]
	s_mov_b32 m0, s50
	s_cmp_lg_u32 s3, 1
	global_load_lds_dwordx4 v132, s[4:5]
	s_cbranch_scc1 .LBB0_519
	s_barrier
	s_setprio 1

; __device__ __forceinline__ int opaque_tid() { int t = threadIdx.x; asm volatile("" : "+v"(t)); return t; }
; #define PG8_STAGE(bufoff, gbase, voff) do { _Pragma("unroll") for (int _i = 0; _i < 2; ++_i) \
;         __builtin_amdgcn_global_load_lds((const unsigned*)((const char*)(gbase) + (voff)[_i]), (LAS unsigned*)(lds + (bufoff) + ldsw + _i * 8192), 16, 0, 0); } while (0)
; #define PG8_WAIT_V(n) asm volatile("s_waitcnt vmcnt(" #n ")" ::: "memory")
; #define PG8_BAR __builtin_amdgcn_s_barrier()
; template <class Epi>
; __device__ __forceinline__ void gemm_phase(LAS unsigned char* lds, const Gemm g, const Epi& E) {
;     const int tid = opaque_tid(), wid = __builtin_amdgcn_readfirstlane(tid >> 6), lane = tid & 63, wr = wid >> 2, wc = wid & 3, fr = lane & 15, fq = lane >> 4;
;     const int K = g.K, nt = K / BK;
;     StaticOrder S; S.init(g.M, g.N, (int)gridDim.x, (int)blockIdx.x);
;     unsigned voffA[2], voffB[2];
; #pragma unroll
;     for (int i = 0; i < 2; ++i) { int R, C; stage_rc(tid * 16 + i * 8192, R, C); const int Rb = Epi::PERM ? ((R & ~31) + perm32(R & 31)) : R;
;         voffA[i] = (unsigned)(R * g.lda + C) * 2u; voffB[i] = (unsigned)(Rb * g.ldb + C) * 2u; }
;     const size_t kstep = (size_t)(BK * 2);
;     const size_t hstepA = (size_t)HALF * g.lda * 2, hstepB = (size_t)HALF * g.ldb * 2;
;     const size_t tstepA = 2 * hstepA, tstepB = 2 * hstepB;
;     const unsigned ldsw = (unsigned)wid * 1024u;
;     const int aoff = lds_byte(wr * 64 + fr, fq * 8), boff = lds_byte(wc * 32 + fr, fq * 8);
;     ...
;     Unit cur, nxt; int ui = 0;
;     if (!S.next(0, cur)) return;
;     f32x4 acc[2][2][4][2];
; #pragma unroll
;     for (int a = 0; a < 2; ++a)
; #pragma unroll
;         for (int b = 0; b < 2; ++b)
; #pragma unroll
;             for (int m = 0; m < 4; ++m)
; #pragma unroll
;                 for (int n = 0; n < 2; ++n) acc[a][b][m][n] = (f32x4){0.f, 0.f, 0.f, 0.f};
;     bf16x8 At[4][2], B0[2][2], B1[2][2];
;     const char* cA = (const char*)g.A + (size_t)g.mapA.src(cur.pm) * tstepA + (size_t)cur.pn * g.a_pn_step;
;     const char* cB = (const char*)g.Bt + (size_t)g.mapB.src(cur.pn) * tstepB;
;     PG8_STAGE(PG8_SB(0, 0), cB, voffB); PG8_STAGE(PG8_SA(0, 0), cA, voffA); PG8_STAGE(PG8_SB(0, 1), cB + hstepB, voffB); PG8_STAGE(PG8_SA(0, 1), cA + hstepA, voffA);
;     if (wr == 1) PG8_BAR;
;     PG8_WAIT_V(4); PG8_BAR;
.LBB0_536:
	s_or_b64 exec, exec, s[2:3]
	v_mov_b32_e32 v10, v210
	s_lshr_b32 s76, s1, 6
	s_barrier
	s_cmp_ge_i32 s37, s76
	s_mov_b32 s5, s1
	v_readfirstlane_b32 s1, v10
	v_readlane_b32 s4, v255, 20
	s_cbranch_scc1 .LBB0_552
	v_lshlrev_b32_e32 v1, 4, v10
	v_add_u32_e32 v3, 0x2000, v1
	v_ashrrev_i32_e32 v2, 31, v3
	v_lshrrev_b32_e32 v2, 22, v2
	v_add_u32_e32 v2, v3, v2
	v_ashrrev_i32_e32 v2, 10, v2
	v_mul_i32_i24_e32 v4, 0x400, v2
	v_sub_u32_e32 v3, v3, v4
	v_lshrrev_b32_e32 v4, 4, v3
	v_bitop3_b32 v5, v4, v3, 32 bitop3:0x6c
	v_ashrrev_i32_e32 v3, 31, v5
	v_lshrrev_b32_e32 v3, 26, v3
	v_add_u32_e32 v6, v5, v3
	v_ashrrev_i32_e32 v3, 6, v6
	v_and_b32_e32 v6, 0xc0, v6
	v_sub_u32_e32 v5, v5, v6
	v_bfe_i32 v6, v10, 27, 1
	v_lshrrev_b32_e32 v6, 22, v6
	v_add_u32_e32 v6, v1, v6
	v_and_b32_e32 v6, 0xfffffc00, v6
	v_sub_u32_e32 v1, v1, v6
	v_lshrrev_b32_e32 v6, 4, v1
	v_lshlrev_b32_e32 v4, 3, v2
	v_bitop3_b32 v9, v6, v1, 32 bitop3:0x6c
	v_ashrrev_i32_e32 v1, 31, v1
	s_mul_hi_u32 s2, s4, 0x580000
	s_mul_i32 s3, s4, 0x580000
	v_readlane_b32 s4, v254, 44
	v_and_b32_e32 v4, 0xfffff0, v4
	v_lshrrev_b32_e32 v1, 26, v1
	s_add_u32 s16, s4, s3
	v_add_u32_e32 v4, v3, v4
	s_movk_i32 s4, 0xb00
	v_add_u32_e32 v1, v9, v1
	v_mul_lo_u32 v7, v4, s4
	v_lshlrev_b32_e32 v4, 5, v2
	v_ashrrev_i32_e32 v6, 6, v1
	v_ashrrev_i32_e32 v1, 31, v10
	v_and_b32_e32 v4, 32, v4
	v_ashrrev_i16_sdwa v5, v219, sext(v5) dst_sel:DWORD dst_unused:UNUSED_PAD src0_sel:DWORD src1_sel:BYTE_0
	v_lshrrev_b32_e32 v1, 26, v1
	v_or_b32_e32 v7, v7, v4
	v_bfe_i32 v5, v5, 0, 16
	v_add_u32_e32 v1, v10, v1
	v_add_lshl_u32 v146, v7, v5, 1
	v_ashrrev_i32_e32 v7, 6, v1
	v_lshlrev_b32_e32 v1, 3, v7
	v_and_b32_e32 v1, 0xfffff0, v1
	v_readlane_b32 s3, v254, 45
	v_add_u32_e32 v1, v6, v1
	s_addc_u32 s17, s3, s2
	v_mul_lo_u32 v1, v1, s4
	s_lshr_b32 s24, s5, 9
	v_readlane_b32 s4, v254, 49
	s_or_b32 s4, s24, s4
	s_mul_i32 s4, s4, s80
	s_add_i32 s4, s4, s75
	s_ashr_i32 s5, s4, 31
	s_lshr_b32 s5, s5, 28
	s_add_i32 s5, s4, s5
	s_ashr_i32 s6, s5, 4
	s_lshl_b32 s6, s6, 2
	s_sub_i32 s7, s28, s6
	s_min_i32 s7, s7, 4
	v_mul_i32_i24_e32 v11, 64, v6
	s_abs_i32 s8, s7
	v_sub_u32_e32 v9, v9, v11
	v_cvt_f32_u32_e32 v11, s8
	v_lshlrev_b32_e32 v8, 5, v7
	v_and_b32_e32 v8, 32, v8
	v_ashrrev_i16_sdwa v9, v219, sext(v9) dst_sel:DWORD dst_unused:UNUSED_PAD src0_sel:DWORD src1_sel:BYTE_0
	v_or_b32_e32 v1, v1, v8
	v_bfe_i32 v9, v9, 0, 16
	v_add_lshl_u32 v148, v1, v9, 1
	v_rcp_iflag_f32_e32 v1, v11
	s_sub_i32 s10, 0, s8
	s_and_b32 s5, s5, -16
	s_sub_i32 s4, s4, s5
	v_mul_f32_e32 v1, 0x4f7ffffe, v1
	v_cvt_u32_f32_e32 v1, v1
	s_abs_i32 s9, s4
	s_ashr_i32 s2, s1, 6
	s_xor_b32 s5, s4, s7
	v_readfirstlane_b32 s11, v1
	s_mul_i32 s10, s10, s11
	s_mul_hi_u32 s10, s11, s10
	s_add_i32 s11, s11, s10
	s_mul_hi_u32 s10, s9, s11
	s_mul_i32 s11, s10, s8
	s_sub_i32 s9, s9, s11
	s_ashr_i32 s3, s1, 8
	s_lshl_b32 s18, s2, 10
	s_ashr_i32 s5, s5, 31
	s_add_i32 s11, s10, 1
	s_sub_i32 s12, s9, s8
	s_cmp_ge_u32 s9, s8
	s_cselect_b32 s10, s11, s10
	s_cselect_b32 s9, s12, s9
	s_add_i32 s11, s10, 1
	s_cmp_ge_u32 s9, s8
	s_cselect_b32 s8, s11, s10
	s_xor_b32 s8, s8, s5
	s_sub_i32 s61, s8, s5
	s_mul_i32 s5, s61, s7
	s_sub_i32 s4, s4, s5
	s_add_i32 s64, s6, s4
	v_readlane_b32 s4, v255, 23
	v_readlane_b32 s5, v255, 24
	s_and_b64 s[4:5], s[4:5], exec
	v_readlane_b32 s4, v255, 27
	s_cselect_b32 s25, 32, -2.0
	s_cmp_ge_i32 s64, s4
	s_cselect_b32 s4, s25, 0
	s_add_i32 s4, s4, s64
	s_mul_i32 s7, s61, 0x160000
	s_mul_hi_i32 s6, s61, 0x160000
	s_add_u32 s10, s16, s7
	s_addc_u32 s11, s17, s6
	s_add_i32 s29, s18, 0
	s_add_i32 m0, s29, 0x10000
	s_mul_hi_i32 s5, s4, 0x160000
	s_mul_i32 s4, s4, 0x160000
	global_load_lds_dwordx4 v148, s[10:11]
	s_add_i32 m0, s29, 0x12000
	s_add_u32 s8, s34, s4
	global_load_lds_dwordx4 v146, s[10:11]
	s_addc_u32 s9, s35, s5
	s_mov_b32 m0, s29
	s_add_i32 s30, s29, 0x2000
	global_load_lds_dwordx4 v148, s[8:9]
	s_mov_b32 m0, s30
	s_add_u32 s4, s10, 0xb0000
	global_load_lds_dwordx4 v146, s[8:9]
	s_addc_u32 s5, s11, 0
	s_add_i32 m0, s29, 0x14000
	s_nop 0
	global_load_lds_dwordx4 v148, s[4:5]
	s_add_i32 m0, s29, 0x16000
	s_nop 0
	global_load_lds_dwordx4 v146, s[4:5]
	s_add_u32 s4, s8, 0xb0000
	s_addc_u32 s5, s9, 0
	s_add_i32 s31, s29, 0x4000
	s_mov_b32 m0, s31
	s_add_i32 s36, s29, 0x6000
	global_load_lds_dwordx4 v148, s[4:5]
	s_mov_b32 m0, s36
	s_cmp_lg_u32 s3, 1
	global_load_lds_dwordx4 v146, s[4:5]
	s_cbranch_scc1 .LBB0_539
	s_barrier
	s_setprio 1

; #define PG8_WAIT_V(n) asm volatile("s_waitcnt vmcnt(" #n ")" ::: "memory")
; #define PG8_BAR __builtin_amdgcn_s_barrier()
; template <class Epi>
; __device__ __forceinline__ void gemm_phase(LAS unsigned char* lds, const Gemm g, const Epi& E) {
;     ...
;     PG8_WAIT_V(0);
;     if (wr == 0) PG8_BAR;
;     PG8_BAR;
.LBB0_551:
	s_setprio 0
	v_readlane_b32 s4, v255, 20
	s_barrier
